# attnC: early barrier arrival before the last four PV MFMAs with wave priority raised until the arrival (on top of the attnA version)
# baseline (speedup 1.0000x reference)
.LBB0_1057:
	v_cmp_le_i32_e32 vcc, s12, v187
	s_and_saveexec_b64 s[10:11], vcc
	s_cbranch_execz .LBB0_1059
	s_lshl_b32 s12, s12, 15
	s_and_b32 s12, s12, 0x8000
	s_add_i32 s12, s80, s12
	s_setprio 1
	v_add3_u32 v220, s12, v186, v190
	v_add_u32_e32 v221, v220, v199
	v_add_u32_e32 v222, v220, v200
	v_add_u32_e32 v223, v220, v201
	v_add_u32_e32 v224, v220, v202
	v_add_u32_e32 v225, v220, v203
	v_add_u32_e32 v226, v220, v216
	v_add_u32_e32 v227, v220, v217
	v_add_u32_e32 v228, v220, v218
	v_lshrrev_b32_e32 v229, v189, v168
	v_lshrrev_b32_e32 v230, v189, v169
	v_add3_u32 v0, s12, v191, v188
	ds_read_b128 v[2:5], v0
	ds_read_b128 v[8:11], v0 offset:8192
	v_add3_u32 v0, s12, v192, v188
	ds_read_b128 v[12:15], v0
	s_waitcnt lgkmcnt(2)
	v_mfma_f32_32x32x16_bf16 v[112:127], v[2:5], v[156:159], v[16:31]
	ds_read_b128 v[2:5], v0 offset:8192
	s_waitcnt lgkmcnt(2)
	v_mfma_f32_32x32x16_bf16 v[96:111], v[8:11], v[156:159], v[16:31]
	v_add3_u32 v0, s12, v193, v188
	ds_read_b128 v[8:11], v0
	s_waitcnt lgkmcnt(2)
	v_mfma_f32_32x32x16_bf16 v[112:127], v[12:15], v[128:131], v[112:127]
	ds_read_b128 v[12:15], v0 offset:8192
	s_waitcnt lgkmcnt(2)
	v_mfma_f32_32x32x16_bf16 v[96:111], v[2:5], v[128:131], v[96:111]
	v_add3_u32 v0, s12, v194, v188
	ds_read_b128 v[2:5], v0
	s_waitcnt lgkmcnt(2)
	v_mfma_f32_32x32x16_bf16 v[112:127], v[8:11], v[132:135], v[112:127]
	ds_read_b128 v[8:11], v0 offset:8192
	s_waitcnt lgkmcnt(2)
	v_mfma_f32_32x32x16_bf16 v[96:111], v[12:15], v[132:135], v[96:111]
	v_add3_u32 v0, s12, v195, v188
	ds_read_b128 v[12:15], v0
	s_waitcnt lgkmcnt(2)
	v_mfma_f32_32x32x16_bf16 v[112:127], v[2:5], v[136:139], v[112:127]
	ds_read_b128 v[2:5], v0 offset:8192
	s_waitcnt lgkmcnt(2)
	v_mfma_f32_32x32x16_bf16 v[96:111], v[8:11], v[136:139], v[96:111]
	v_add3_u32 v0, s12, v196, v188
	ds_read_b128 v[8:11], v0
	s_waitcnt lgkmcnt(2)
	v_mfma_f32_32x32x16_bf16 v[112:127], v[12:15], v[140:143], v[112:127]
	ds_read_b128 v[12:15], v0 offset:8192
	s_waitcnt lgkmcnt(2)
	v_mfma_f32_32x32x16_bf16 v[96:111], v[2:5], v[140:143], v[96:111]
	v_add3_u32 v0, s12, v197, v188
	ds_read_b128 v[2:5], v0
	s_waitcnt lgkmcnt(2)
	v_mfma_f32_32x32x16_bf16 v[112:127], v[8:11], v[144:147], v[112:127]
	ds_read_b128 v[8:11], v0 offset:8192
	s_waitcnt lgkmcnt(2)
	v_mfma_f32_32x32x16_bf16 v[96:111], v[12:15], v[144:147], v[96:111]
	v_add3_u32 v0, s12, v198, v188
	ds_read_b128 v[12:15], v0
	s_waitcnt lgkmcnt(2)
	v_mfma_f32_32x32x16_bf16 v[112:127], v[2:5], v[148:151], v[112:127]
	ds_read_b128 v[2:5], v0 offset:8192
	s_waitcnt lgkmcnt(2)
	v_mfma_f32_32x32x16_bf16 v[96:111], v[8:11], v[148:151], v[96:111]
	s_waitcnt lgkmcnt(1)
	v_mfma_f32_32x32x16_bf16 v[112:127], v[12:15], v[152:155], v[112:127]
	s_waitcnt lgkmcnt(0)
	v_mfma_f32_32x32x16_bf16 v[96:111], v[2:5], v[152:155], v[96:111]
	ds_read_b64 v[8:9], v221 offset:16384
	ds_read_b64 v[10:11], v222 offset:16384
	ds_read_b64 v[12:13], v221 offset:20480
	ds_read_b64 v[14:15], v222 offset:20480
	ds_read_b64 v[236:237], v221 offset:28672
	ds_read_b64 v[238:239], v222 offset:28672
	s_nop 3
	v_exp_f32_e32 v112, v112
	v_exp_f32_e32 v113, v113
	v_exp_f32_e32 v114, v114
	v_exp_f32_e32 v115, v115
	v_exp_f32_e32 v116, v116
	v_exp_f32_e32 v117, v117
	v_exp_f32_e32 v118, v118
	v_exp_f32_e32 v119, v119
	v_bfe_i32 v231, v229, 0, 1
	v_and_b32_e32 v112, v112, v231
	v_bfe_i32 v232, v229, 1, 1
	v_and_b32_e32 v113, v113, v232
	v_bfe_i32 v231, v229, 2, 1
	v_and_b32_e32 v114, v114, v231
	v_bfe_i32 v232, v229, 3, 1
	v_and_b32_e32 v115, v115, v232
	v_bfe_i32 v231, v229, 8, 1
	v_and_b32_e32 v116, v116, v231
	v_bfe_i32 v232, v229, 9, 1
	v_and_b32_e32 v117, v117, v232
	v_bfe_i32 v231, v229, 10, 1
	v_and_b32_e32 v118, v118, v231
	v_bfe_i32 v232, v229, 11, 1
	v_and_b32_e32 v119, v119, v232
	v_cvt_pk_bf16_f32 v2, v112, v113
	v_cvt_pk_bf16_f32 v3, v114, v115
	v_cvt_pk_bf16_f32 v4, v116, v117
	v_cvt_pk_bf16_f32 v5, v118, v119
	v_add_f32_e32 v0, 0, v112
	v_add_f32_e32 v0, v113, v0
	v_add_f32_e32 v0, v114, v0
	v_add_f32_e32 v0, v115, v0
	v_add_f32_e32 v0, v116, v0
	v_add_f32_e32 v0, v117, v0
	v_add_f32_e32 v0, v118, v0
	v_add_f32_e32 v0, v119, v0
	ds_read_b64 v[240:241], v221 offset:24576
	ds_read_b64 v[242:243], v222 offset:24576
	ds_read_b64 v[244:245], v223 offset:16384
	ds_read_b64 v[246:247], v224 offset:16384
	s_waitcnt lgkmcnt(8)
	v_mfma_f32_32x32x16_bf16 v[80:95], v[8:11], v[2:5], v[80:95]
	ds_read_b64 v[112:113], v223 offset:20480
	ds_read_b64 v[114:115], v224 offset:20480
	v_exp_f32_e32 v120, v120
	v_exp_f32_e32 v121, v121
	s_waitcnt lgkmcnt(8)
	v_mfma_f32_32x32x16_bf16 v[64:79], v[12:15], v[2:5], v[64:79]
	ds_read_b64 v[116:117], v223 offset:24576
	ds_read_b64 v[118:119], v224 offset:24576
	v_exp_f32_e32 v122, v122
	v_exp_f32_e32 v123, v123
	v_bfe_i32 v231, v229, 16, 1
	v_and_b32_e32 v120, v120, v231
	v_bfe_i32 v232, v229, 17, 1
	v_and_b32_e32 v121, v121, v232
	v_add_f32_e32 v0, v120, v0
	v_add_f32_e32 v0, v121, v0
	s_waitcnt lgkmcnt(8)
	v_mfma_f32_32x32x16_bf16 v[32:47], v[236:239], v[2:5], v[32:47]
	ds_read_b64 v[8:9], v223 offset:28672
	ds_read_b64 v[10:11], v224 offset:28672
	v_exp_f32_e32 v124, v124
	v_exp_f32_e32 v125, v125
	v_bfe_i32 v231, v229, 18, 1
	v_and_b32_e32 v122, v122, v231
	v_bfe_i32 v232, v229, 19, 1
	v_and_b32_e32 v123, v123, v232
	v_add_f32_e32 v0, v122, v0
	v_add_f32_e32 v0, v123, v0
	s_waitcnt lgkmcnt(8)
	v_mfma_f32_32x32x16_bf16 v[48:63], v[240:243], v[2:5], v[48:63]
	ds_read_b64 v[12:13], v225 offset:16384
	ds_read_b64 v[14:15], v226 offset:16384
	v_exp_f32_e32 v126, v126
	v_exp_f32_e32 v127, v127
	v_bfe_i32 v231, v229, 24, 1
	v_and_b32_e32 v124, v124, v231
	v_bfe_i32 v232, v229, 25, 1
	v_and_b32_e32 v125, v125, v232
	v_add_f32_e32 v0, v124, v0
	v_add_f32_e32 v0, v125, v0
	v_bfe_i32 v231, v229, 26, 1
	v_and_b32_e32 v126, v126, v231
	v_bfe_i32 v232, v229, 27, 1
	v_and_b32_e32 v127, v127, v232
	v_add_f32_e32 v0, v126, v0
	v_add_f32_e32 v0, v127, v0
	v_cvt_pk_bf16_f32 v2, v120, v121
	v_cvt_pk_bf16_f32 v3, v122, v123
	v_cvt_pk_bf16_f32 v4, v124, v125
	v_cvt_pk_bf16_f32 v5, v126, v127
	s_nop 1
	ds_read_b64 v[236:237], v225 offset:20480
	ds_read_b64 v[238:239], v226 offset:20480
	s_waitcnt lgkmcnt(10)
	v_mfma_f32_32x32x16_bf16 v[80:95], v[244:247], v[2:5], v[80:95]
	ds_read_b64 v[240:241], v225 offset:24576
	ds_read_b64 v[242:243], v226 offset:24576
	v_exp_f32_e32 v96, v96
	v_exp_f32_e32 v97, v97
	s_waitcnt lgkmcnt(10)
	v_mfma_f32_32x32x16_bf16 v[64:79], v[112:115], v[2:5], v[64:79]
	ds_read_b64 v[120:121], v225 offset:28672
	ds_read_b64 v[122:123], v226 offset:28672
	v_exp_f32_e32 v98, v98
	v_exp_f32_e32 v99, v99
	v_bfe_i32 v231, v230, 0, 1
	v_and_b32_e32 v96, v96, v231
	v_bfe_i32 v232, v230, 1, 1
	v_and_b32_e32 v97, v97, v232
	v_add_f32_e32 v0, v96, v0
	v_add_f32_e32 v0, v97, v0
	s_waitcnt lgkmcnt(10)
	v_mfma_f32_32x32x16_bf16 v[48:63], v[116:119], v[2:5], v[48:63]
	ds_read_b64 v[124:125], v227 offset:16384
	ds_read_b64 v[126:127], v228 offset:16384
	v_exp_f32_e32 v100, v100
	v_exp_f32_e32 v101, v101
	v_bfe_i32 v231, v230, 2, 1
	v_and_b32_e32 v98, v98, v231
	v_bfe_i32 v232, v230, 3, 1
	v_and_b32_e32 v99, v99, v232
	v_add_f32_e32 v0, v98, v0
	v_add_f32_e32 v0, v99, v0
	s_waitcnt lgkmcnt(10)
	v_mfma_f32_32x32x16_bf16 v[32:47], v[8:11], v[2:5], v[32:47]
	ds_read_b64 v[244:245], v227 offset:20480
	ds_read_b64 v[246:247], v228 offset:20480
	v_exp_f32_e32 v102, v102
	v_exp_f32_e32 v103, v103
	v_bfe_i32 v231, v230, 8, 1
	v_and_b32_e32 v100, v100, v231
	v_bfe_i32 v232, v230, 9, 1
	v_and_b32_e32 v101, v101, v232
	v_add_f32_e32 v0, v100, v0
	v_add_f32_e32 v0, v101, v0
	v_bfe_i32 v231, v230, 10, 1
	v_and_b32_e32 v102, v102, v231
	v_bfe_i32 v232, v230, 11, 1
	v_and_b32_e32 v103, v103, v232
	v_add_f32_e32 v0, v102, v0
	v_add_f32_e32 v0, v103, v0
	v_cvt_pk_bf16_f32 v2, v96, v97
	v_cvt_pk_bf16_f32 v3, v98, v99
	v_cvt_pk_bf16_f32 v4, v100, v101
	v_cvt_pk_bf16_f32 v5, v102, v103
	s_nop 1
	ds_read_b64 v[112:113], v227 offset:24576
	ds_read_b64 v[114:115], v228 offset:24576
	s_waitcnt lgkmcnt(12)
	v_mfma_f32_32x32x16_bf16 v[80:95], v[12:15], v[2:5], v[80:95]
	ds_read_b64 v[116:117], v227 offset:28672
	ds_read_b64 v[118:119], v228 offset:28672
	v_exp_f32_e32 v104, v104
	v_exp_f32_e32 v105, v105
	s_waitcnt lgkmcnt(12)
	v_mfma_f32_32x32x16_bf16 v[64:79], v[236:239], v[2:5], v[64:79]
	v_exp_f32_e32 v106, v106
	v_exp_f32_e32 v107, v107
	v_bfe_i32 v231, v230, 16, 1
	v_and_b32_e32 v104, v104, v231
	v_bfe_i32 v232, v230, 17, 1
	v_and_b32_e32 v105, v105, v232
	v_add_f32_e32 v0, v104, v0
	v_add_f32_e32 v0, v105, v0
	s_waitcnt lgkmcnt(10)
	v_mfma_f32_32x32x16_bf16 v[48:63], v[240:243], v[2:5], v[48:63]
	v_exp_f32_e32 v108, v108
	v_exp_f32_e32 v109, v109
	v_bfe_i32 v231, v230, 18, 1
	v_and_b32_e32 v106, v106, v231
	v_bfe_i32 v232, v230, 19, 1
	v_and_b32_e32 v107, v107, v232
	v_add_f32_e32 v0, v106, v0
	v_add_f32_e32 v0, v107, v0
	s_waitcnt lgkmcnt(8)
	v_mfma_f32_32x32x16_bf16 v[32:47], v[120:123], v[2:5], v[32:47]
	v_exp_f32_e32 v110, v110
	v_exp_f32_e32 v111, v111
	v_bfe_i32 v231, v230, 24, 1
	v_and_b32_e32 v108, v108, v231
	v_bfe_i32 v232, v230, 25, 1
	v_and_b32_e32 v109, v109, v232
	v_add_f32_e32 v0, v108, v0
	v_add_f32_e32 v0, v109, v0
	v_bfe_i32 v231, v230, 26, 1
	v_and_b32_e32 v110, v110, v231
	v_bfe_i32 v232, v230, 27, 1
	v_and_b32_e32 v111, v111, v232
	v_add_f32_e32 v0, v110, v0
	v_add_f32_e32 v0, v111, v0
	v_cvt_pk_bf16_f32 v2, v104, v105
	v_cvt_pk_bf16_f32 v3, v106, v107
	v_cvt_pk_bf16_f32 v4, v108, v109
	v_cvt_pk_bf16_f32 v5, v110, v111
	s_nop 1
	s_waitcnt vmcnt(0) lgkmcnt(0)
	s_mov_b64 s[24:25], exec
	s_mov_b64 exec, 1
	v_mov_b32_e32 v248, s33
	v_mov_b32_e32 v249, 1
	ds_add_u32 v248, v249 offset:8
	s_mov_b64 exec, s[24:25]
	s_setprio 0
	s_waitcnt lgkmcnt(6)
	v_mfma_f32_32x32x16_bf16 v[80:95], v[124:127], v[2:5], v[80:95]
	s_waitcnt lgkmcnt(4)
	v_mfma_f32_32x32x16_bf16 v[64:79], v[244:247], v[2:5], v[64:79]
	s_waitcnt lgkmcnt(2)
	v_mfma_f32_32x32x16_bf16 v[48:63], v[112:115], v[2:5], v[48:63]
	s_waitcnt lgkmcnt(0)
	v_mfma_f32_32x32x16_bf16 v[32:47], v[116:119], v[2:5], v[32:47]
	v_add_f32_e32 v219, v219, v0
	s_branch .LBB0_1062
